# slc unit epilogue: loads of groups 1-3 and 5-7 hoisted behind groups 0 and 4, vmcnt recomputed
# baseline (speedup 1.0000x reference)
; DI unsigned pack2(float a, float b) { f32x2 v = {a, b}; bf16x2_t r = __builtin_convertvector(v, bf16x2_t); return __builtin_bit_cast(unsigned, r); }
; DI float bflo(unsigned v) { return __uint_as_float(v << 16); }
; DI float bfhi(unsigned v) { return __uint_as_float(v & 0xffff0000u); }
; DI size_t blk(size_t row, int k, int R) { return ((size_t)(k >> 5) * R + row) * 32 + (k & 31); }
; DI float silu_f(float x) { return x / (1.f + __expf(-x)); }
; DI void nsa_slc_unit(const Params& p, int u, char* smem, bool probe = false) {
;     ...
;   l += __shfl_xor(l, 32);
;   const float inv = 1.f / l;
;   const float g0 = p.gates[tok * 48 + head * 3], g1 = p.gates[tok * 48 + head * 3 + 1] * inv, g2 = p.gates[tok * 48 + head * 3 + 2];
;   const bf16_t* oc = p.Q + (size_t)NTOK * 1024 + tok * 1024 + head * 64; const bf16_t* ow = p.Q + (size_t)2 * NTOK * 1024 + tok * 1024 + head * 64;
; #pragma unroll
;   for (int dt = 0; dt < 2; ++dt)
; #pragma unroll
;     for (int g4 = 0; g4 < 4; ++g4) {
;       const int d = 32 * dt + 8 * g4 + 4 * h;
;       bf16_t* gp = p.G + blk(tok, head * 64 + d, NTOK);
;       const u32x2 cv = *(const u32x2*)(oc + d), wv = *(const u32x2*)(ow + d), gv = *(const u32x2*)gp;
;       const float a0 = (g0 * bflo(cv[0]) + g1 * o[dt][4 * g4] + g2 * bflo(wv[0])) * silu_f(bflo(gv[0]));
;       const float a1 = (g0 * bfhi(cv[0]) + g1 * o[dt][4 * g4 + 1] + g2 * bfhi(wv[0])) * silu_f(bfhi(gv[0]));
;       const float a2 = (g0 * bflo(cv[1]) + g1 * o[dt][4 * g4 + 2] + g2 * bflo(wv[1])) * silu_f(bflo(gv[1]));
;       const float a3 = (g0 * bfhi(cv[1]) + g1 * o[dt][4 * g4 + 3] + g2 * bfhi(wv[1])) * silu_f(bfhi(gv[1]));
;       *(u32x2*)gp = (u32x2){pack2(a0, a1), pack2(a2, a3)};
;     }
.LBB0_812:
	v_and_b32_e32 v34, 64, v202
	v_xor_b32_e32 v0, 32, v202
	v_add_u32_e32 v34, 64, v34
	v_cmp_lt_i32_e32 vcc, v0, v34
	v_readlane_b32 s36, v230, 51
	v_readlane_b32 s44, v230, 59
	v_cndmask_b32_e32 v0, v202, v0, vcc
	v_lshlrev_b32_e32 v0, 2, v0
	ds_bpermute_b32 v0, v0, v213
	v_readlane_b32 s45, v230, 60
	s_movk_i32 s4, 0xc0
	v_lshlrev_b64 v[40:41], 1, v[182:183]
	v_mov_b32_e32 v185, v1
	s_waitcnt lgkmcnt(0)
	v_add_f32_e32 v0, v213, v0
	v_div_scale_f32 v34, s[2:3], v0, v0, 1.0
	v_rcp_f32_e32 v35, v34
	v_lshrrev_b32_e32 v37, 3, v210
	v_readlane_b32 s38, v230, 53
	v_readlane_b32 s39, v230, 54
	v_fma_f32 v36, -v34, v35, 1.0
	v_fmac_f32_e32 v35, v36, v35
	v_div_scale_f32 v36, vcc, 1.0, v0, 1.0
	v_mul_f32_e32 v38, v36, v35
	v_fma_f32 v39, -v34, v38, v36
	v_fmac_f32_e32 v38, v39, v35
	v_fma_f32 v34, -v34, v38, v36
	v_div_fmas_f32 v34, v34, v35, v38
	v_div_fixup_f32 v38, v34, v0, 1.0
	v_mov_b64_e32 v[34:35], s[44:45]
	v_mad_u64_u32 v[34:35], s[2:3], v180, s4, v[34:35]
	v_readlane_b32 s2, v229, 3
	v_readlane_b32 s3, v229, 4
	v_mul_u32_u24_e32 v0, 3, v209
	v_mad_i32_i24 v35, v181, s4, v35
	v_lshl_add_u64 v[42:43], s[2:3], 0, v[40:41]
	v_readlane_b32 s2, v230, 16
	v_lshlrev_b32_e32 v0, 2, v0
	v_readlane_b32 s3, v230, 17
	v_lshl_add_u64 v[34:35], v[34:35], 0, v[0:1]
	v_lshlrev_b32_e32 v0, 16, v209
	v_lshl_add_u64 v[40:41], s[2:3], 0, v[40:41]
	v_lshl_add_u64 v[48:49], v[40:41], 0, v[184:185]
	v_lshl_add_u64 v[40:41], v[180:181], 0, v[0:1]
	v_and_b32_e32 v37, 4, v37
	v_lshlrev_b64 v[40:41], 6, v[40:41]
	v_lshl_add_u64 v[42:43], v[42:43], 0, v[184:185]
	v_lshl_add_u64 v[40:41], s[38:39], 0, v[40:41]
	v_lshlrev_b32_e32 v44, 1, v37
	v_mov_b32_e32 v45, v1
	v_lshl_add_u64 v[46:47], v[40:41], 0, v[44:45]
	v_lshl_add_u64 v[40:41], v[42:43], 0, v[44:45]
	global_load_dwordx2 v[50:51], v[40:41], off
	v_lshl_add_u64 v[42:43], v[48:49], 0, v[44:45]
	global_load_dwordx3 v[34:36], v[34:35], off
	s_nop 0
	global_load_dwordx2 v[48:49], v[42:43], off
	global_load_dwordx2 v[52:53], v[46:47], off
	global_load_dwordx2 v[232:233], v[40:41], off offset:16
	global_load_dwordx2 v[234:235], v[42:43], off offset:16
	global_load_dwordx2 v[236:237], v[46:47], off offset:16
	global_load_dwordx2 v[238:239], v[40:41], off offset:32
	global_load_dwordx2 v[240:241], v[42:43], off offset:32
	global_load_dwordx2 v[242:243], v[46:47], off offset:32
	global_load_dwordx2 v[244:245], v[40:41], off offset:48
	global_load_dwordx2 v[246:247], v[42:43], off offset:48
	global_load_dwordx2 v[248:249], v[46:47], off offset:48
	v_or_b32_e32 v0, 0x8000, v0
	s_add_i32 s1, s1, s82
	s_cmpk_lt_i32 s1, 0x1000
	v_readlane_b32 s37, v230, 52
	v_readlane_b32 s40, v230, 55
	v_readlane_b32 s41, v230, 56
	v_readlane_b32 s42, v230, 57
	v_readlane_b32 s43, v230, 58
	v_readlane_b32 s46, v230, 61
	v_readlane_b32 s47, v230, 62
	v_readlane_b32 s48, v230, 63
	v_readlane_b32 s49, v229, 0
	v_readlane_b32 s50, v229, 1
	v_readlane_b32 s51, v229, 2
	s_waitcnt vmcnt(12)
	v_lshlrev_b32_e32 v56, 16, v50
	v_and_b32_e32 v57, 0xffff0000, v50
	s_waitcnt vmcnt(11)
	v_mul_f32_e32 v38, v35, v38
	s_waitcnt vmcnt(9)
	v_lshlrev_b32_e32 v39, 16, v52
	v_pk_mul_f32 v[56:57], v[34:35], v[56:57] op_sel_hi:[0,1]
	v_and_b32_e32 v52, 0xffff0000, v52
	v_mul_f32_e32 v37, 0xbfb8aa3b, v39
	v_pk_fma_f32 v[56:57], v[2:3], v[38:39], v[56:57] op_sel_hi:[1,0,1]
	v_lshlrev_b32_e32 v58, 16, v48
	v_and_b32_e32 v59, 0xffff0000, v48
	v_mov_b32_e32 v2, v36
	v_exp_f32_e32 v54, v37
	v_pk_fma_f32 v[36:37], v[2:3], v[58:59], v[56:57] op_sel_hi:[0,1,1]
	v_mul_f32_e32 v3, 0xbfb8aa3b, v52
	v_exp_f32_e32 v55, v3
	s_nop 0
	v_pk_add_f32 v[54:55], v[54:55], 1.0 op_sel_hi:[1,0]
	s_nop 0
	v_div_scale_f32 v3, s[2:3], v55, v55, v52
	v_rcp_f32_e32 v48, v3
	s_nop 0
	v_fma_f32 v50, -v3, v48, 1.0
	v_fmac_f32_e32 v48, v50, v48
	v_div_scale_f32 v50, vcc, v52, v55, v52
	v_mul_f32_e32 v56, v50, v48
	v_fma_f32 v57, -v3, v56, v50
	v_fmac_f32_e32 v56, v57, v48
	v_fma_f32 v3, -v3, v56, v50
	v_div_fmas_f32 v3, v3, v48, v56
	v_div_fixup_f32 v55, v3, v55, v52
	v_div_scale_f32 v3, s[2:3], v54, v54, v39
	v_rcp_f32_e32 v48, v3
	s_nop 0
	v_fma_f32 v50, -v3, v48, 1.0
	v_fmac_f32_e32 v48, v50, v48
	v_div_scale_f32 v50, vcc, v39, v54, v39
	v_mul_f32_e32 v52, v50, v48
	v_fma_f32 v56, -v3, v52, v50
	v_fmac_f32_e32 v52, v56, v48
	v_fma_f32 v3, -v3, v52, v50
	v_div_fmas_f32 v3, v3, v48, v52
	v_lshlrev_b32_e32 v50, 16, v51
	v_and_b32_e32 v51, 0xffff0000, v51
	v_div_fixup_f32 v54, v3, v54, v39
	v_lshlrev_b32_e32 v3, 16, v53
	v_and_b32_e32 v39, 0xffff0000, v53
	v_pk_mul_f32 v[50:51], v[34:35], v[50:51] op_sel_hi:[0,1]
	v_mul_f32_e32 v48, 0xbfb8aa3b, v3
	v_pk_fma_f32 v[4:5], v[4:5], v[38:39], v[50:51] op_sel_hi:[1,0,1]
	v_lshlrev_b32_e32 v50, 16, v49
	v_and_b32_e32 v51, 0xffff0000, v49
	v_mul_f32_e32 v49, 0xbfb8aa3b, v39
	v_exp_f32_e32 v48, v48
	v_exp_f32_e32 v49, v49
	v_pk_fma_f32 v[4:5], v[2:3], v[50:51], v[4:5] op_sel_hi:[0,1,1]
	v_pk_mul_f32 v[36:37], v[36:37], v[54:55]
	v_pk_add_f32 v[48:49], v[48:49], 1.0 op_sel_hi:[1,0]
	s_nop 0
	v_div_scale_f32 v50, s[2:3], v49, v49, v39
	v_rcp_f32_e32 v51, v50
	v_cvt_pk_bf16_f32 v36, v36, v37
	v_fma_f32 v52, -v50, v51, 1.0
	v_fmac_f32_e32 v51, v52, v51
	v_div_scale_f32 v52, vcc, v39, v49, v39
	v_mul_f32_e32 v53, v52, v51
	v_fma_f32 v54, -v50, v53, v52
	v_fmac_f32_e32 v53, v54, v51
	v_fma_f32 v50, -v50, v53, v52
	v_div_fmas_f32 v50, v50, v51, v53
	v_div_fixup_f32 v49, v50, v49, v39
	v_div_scale_f32 v39, s[2:3], v48, v48, v3
	v_rcp_f32_e32 v50, v39
	s_nop 0
	v_fma_f32 v51, -v39, v50, 1.0
	v_fmac_f32_e32 v50, v51, v50
	v_div_scale_f32 v51, vcc, v3, v48, v3
	v_mul_f32_e32 v52, v51, v50
	v_fma_f32 v53, -v39, v52, v51
	v_fmac_f32_e32 v52, v53, v50
	v_fma_f32 v39, -v39, v52, v51
	v_div_fmas_f32 v39, v39, v50, v52
	v_div_fixup_f32 v48, v39, v48, v3
	v_pk_mul_f32 v[4:5], v[4:5], v[48:49]
	s_nop 0
	v_cvt_pk_bf16_f32 v37, v4, v5
	global_store_dwordx2 v[46:47], v[36:37], off
	s_nop 0
	s_waitcnt vmcnt(9)
; DI unsigned pack2(float a, float b) { f32x2 v = {a, b}; bf16x2_t r = __builtin_convertvector(v, bf16x2_t); return __builtin_bit_cast(unsigned, r); }
; DI float bflo(unsigned v) { return __uint_as_float(v << 16); }
; DI float bfhi(unsigned v) { return __uint_as_float(v & 0xffff0000u); }
; DI size_t blk(size_t row, int k, int R) { return ((size_t)(k >> 5) * R + row) * 32 + (k & 31); }
; DI float silu_f(float x) { return x / (1.f + __expf(-x)); }
; DI void nsa_slc_unit(const Params& p, int u, char* smem, bool probe = false) {
;     ...
;       const int d = 32 * dt + 8 * g4 + 4 * h;
;       bf16_t* gp = p.G + blk(tok, head * 64 + d, NTOK);
;       const u32x2 cv = *(const u32x2*)(oc + d), wv = *(const u32x2*)(ow + d), gv = *(const u32x2*)gp;
;       const float a0 = (g0 * bflo(cv[0]) + g1 * o[dt][4 * g4] + g2 * bflo(wv[0])) * silu_f(bflo(gv[0]));
;       const float a1 = (g0 * bfhi(cv[0]) + g1 * o[dt][4 * g4 + 1] + g2 * bfhi(wv[0])) * silu_f(bfhi(gv[0]));
;       const float a2 = (g0 * bflo(cv[1]) + g1 * o[dt][4 * g4 + 2] + g2 * bflo(wv[1])) * silu_f(bflo(gv[1]));
;       const float a3 = (g0 * bfhi(cv[1]) + g1 * o[dt][4 * g4 + 3] + g2 * bfhi(wv[1])) * silu_f(bfhi(gv[1]));
;       *(u32x2*)gp = (u32x2){pack2(a0, a1), pack2(a2, a3)};
	v_mov_b32_e32 v36, v232
	v_mov_b32_e32 v37, v233
	v_lshlrev_b32_e32 v52, 16, v36
	v_and_b32_e32 v53, 0xffff0000, v36
	s_waitcnt vmcnt(7)
	v_mov_b32_e32 v4, v234
	v_mov_b32_e32 v5, v235
	v_mov_b32_e32 v48, v236
	v_mov_b32_e32 v49, v237
	v_lshlrev_b32_e32 v3, 16, v48
	v_and_b32_e32 v39, 0xffff0000, v48
	v_pk_mul_f32 v[52:53], v[34:35], v[52:53] op_sel_hi:[0,1]
	v_mul_f32_e32 v48, 0xbfb8aa3b, v3
	v_pk_fma_f32 v[6:7], v[6:7], v[38:39], v[52:53] op_sel_hi:[1,0,1]
	v_lshlrev_b32_e32 v52, 16, v4
	v_and_b32_e32 v53, 0xffff0000, v4
	v_mul_f32_e32 v4, 0xbfb8aa3b, v39
	v_exp_f32_e32 v50, v48
	v_exp_f32_e32 v51, v4
	v_pk_fma_f32 v[6:7], v[2:3], v[52:53], v[6:7] op_sel_hi:[0,1,1]
	v_pk_add_f32 v[50:51], v[50:51], 1.0 op_sel_hi:[1,0]
	s_nop 0
	v_div_scale_f32 v4, s[2:3], v51, v51, v39
	v_rcp_f32_e32 v36, v4
	s_nop 0
	v_fma_f32 v48, -v4, v36, 1.0
	v_fmac_f32_e32 v36, v48, v36
	v_div_scale_f32 v48, vcc, v39, v51, v39
	v_mul_f32_e32 v52, v48, v36
	v_fma_f32 v53, -v4, v52, v48
	v_fmac_f32_e32 v52, v53, v36
	v_fma_f32 v4, -v4, v52, v48
	v_div_fmas_f32 v4, v4, v36, v52
	v_div_fixup_f32 v51, v4, v51, v39
	v_div_scale_f32 v4, s[2:3], v50, v50, v3
	v_rcp_f32_e32 v36, v4
	s_nop 0
	v_fma_f32 v39, -v4, v36, 1.0
	v_fmac_f32_e32 v36, v39, v36
	v_div_scale_f32 v39, vcc, v3, v50, v3
	v_mul_f32_e32 v48, v39, v36
	v_fma_f32 v52, -v4, v48, v39
	v_fmac_f32_e32 v48, v52, v36
	v_fma_f32 v4, -v4, v48, v39
	v_div_fmas_f32 v4, v4, v36, v48
	v_lshlrev_b32_e32 v36, 16, v37
	v_and_b32_e32 v37, 0xffff0000, v37
	v_div_fixup_f32 v50, v4, v50, v3
	v_lshlrev_b32_e32 v3, 16, v49
	v_and_b32_e32 v39, 0xffff0000, v49
	v_pk_mul_f32 v[36:37], v[34:35], v[36:37] op_sel_hi:[0,1]
	v_mul_f32_e32 v4, 0xbfb8aa3b, v3
	v_pk_fma_f32 v[8:9], v[8:9], v[38:39], v[36:37] op_sel_hi:[1,0,1]
	v_lshlrev_b32_e32 v36, 16, v5
	v_and_b32_e32 v37, 0xffff0000, v5
	v_mul_f32_e32 v5, 0xbfb8aa3b, v39
	v_exp_f32_e32 v4, v4
	v_exp_f32_e32 v5, v5
	v_pk_fma_f32 v[8:9], v[2:3], v[36:37], v[8:9] op_sel_hi:[0,1,1]
	v_pk_mul_f32 v[6:7], v[6:7], v[50:51]
	v_pk_add_f32 v[4:5], v[4:5], 1.0 op_sel_hi:[1,0]
	s_nop 0
	v_div_scale_f32 v36, s[2:3], v5, v5, v39
	v_rcp_f32_e32 v37, v36
	v_cvt_pk_bf16_f32 v6, v6, v7
	v_fma_f32 v48, -v36, v37, 1.0
	v_fmac_f32_e32 v37, v48, v37
	v_div_scale_f32 v48, vcc, v39, v5, v39
	v_mul_f32_e32 v49, v48, v37
	v_fma_f32 v50, -v36, v49, v48
	v_fmac_f32_e32 v49, v50, v37
	v_fma_f32 v36, -v36, v49, v48
	v_div_fmas_f32 v36, v36, v37, v49
	v_div_fixup_f32 v5, v36, v5, v39
	v_div_scale_f32 v36, s[2:3], v4, v4, v3
	v_rcp_f32_e32 v37, v36
	s_nop 0
	v_fma_f32 v39, -v36, v37, 1.0
	v_fmac_f32_e32 v37, v39, v37
	v_div_scale_f32 v39, vcc, v3, v4, v3
	v_mul_f32_e32 v48, v39, v37
	v_fma_f32 v49, -v36, v48, v39
	v_fmac_f32_e32 v48, v49, v37
	v_fma_f32 v36, -v36, v48, v39
	v_div_fmas_f32 v36, v36, v37, v48
	v_div_fixup_f32 v4, v36, v4, v3
	v_pk_mul_f32 v[4:5], v[8:9], v[4:5]
	s_nop 0
	v_cvt_pk_bf16_f32 v7, v4, v5
	global_store_dwordx2 v[46:47], v[6:7], off offset:16
	s_nop 0
	s_waitcnt vmcnt(7)
	v_mov_b32_e32 v6, v238
	v_mov_b32_e32 v7, v239
	v_lshlrev_b32_e32 v48, 16, v6
	v_and_b32_e32 v49, 0xffff0000, v6
	s_waitcnt vmcnt(5)
	v_mov_b32_e32 v4, v240
	v_mov_b32_e32 v5, v241
	v_mov_b32_e32 v8, v242
	v_mov_b32_e32 v9, v243
	v_lshlrev_b32_e32 v3, 16, v8
	v_and_b32_e32 v8, 0xffff0000, v8
	v_pk_mul_f32 v[48:49], v[34:35], v[48:49] op_sel_hi:[0,1]
	v_mul_f32_e32 v36, 0xbfb8aa3b, v3
	v_pk_fma_f32 v[10:11], v[10:11], v[38:39], v[48:49] op_sel_hi:[1,0,1]
	v_lshlrev_b32_e32 v48, 16, v4
	v_and_b32_e32 v49, 0xffff0000, v4
	v_mul_f32_e32 v4, 0xbfb8aa3b, v8
	v_exp_f32_e32 v36, v36
	v_exp_f32_e32 v37, v4
	v_pk_fma_f32 v[10:11], v[2:3], v[48:49], v[10:11] op_sel_hi:[0,1,1]
	v_pk_add_f32 v[36:37], v[36:37], 1.0 op_sel_hi:[1,0]
	s_nop 0
	v_div_scale_f32 v4, s[2:3], v37, v37, v8
	v_rcp_f32_e32 v6, v4
	s_nop 0
	v_fma_f32 v39, -v4, v6, 1.0
	v_fmac_f32_e32 v6, v39, v6
	v_div_scale_f32 v39, vcc, v8, v37, v8
	v_mul_f32_e32 v48, v39, v6
	v_fma_f32 v49, -v4, v48, v39
	v_fmac_f32_e32 v48, v49, v6
	v_fma_f32 v4, -v4, v48, v39
	v_div_fmas_f32 v4, v4, v6, v48
	v_div_fixup_f32 v37, v4, v37, v8
	v_div_scale_f32 v4, s[2:3], v36, v36, v3
	v_rcp_f32_e32 v6, v4
	s_nop 0
	v_fma_f32 v8, -v4, v6, 1.0
	v_fmac_f32_e32 v6, v8, v6
	v_div_scale_f32 v8, vcc, v3, v36, v3
	v_mul_f32_e32 v39, v8, v6
	v_fma_f32 v48, -v4, v39, v8
	v_fmac_f32_e32 v39, v48, v6
	v_fma_f32 v4, -v4, v39, v8
	v_div_fmas_f32 v4, v4, v6, v39
	v_div_fixup_f32 v36, v4, v36, v3
	v_pk_mul_f32 v[10:11], v[10:11], v[36:37]
	v_lshlrev_b32_e32 v3, 16, v9
	v_and_b32_e32 v36, 0xffff0000, v9
	v_mul_f32_e32 v4, 0xbfb8aa3b, v3
	v_lshlrev_b32_e32 v8, 16, v5
	v_and_b32_e32 v9, 0xffff0000, v5
	v_mul_f32_e32 v5, 0xbfb8aa3b, v36
	v_exp_f32_e32 v4, v4
	v_exp_f32_e32 v5, v5
	v_lshlrev_b32_e32 v6, 16, v7
	v_and_b32_e32 v7, 0xffff0000, v7
	v_pk_mul_f32 v[6:7], v[34:35], v[6:7] op_sel_hi:[0,1]
	v_pk_fma_f32 v[6:7], v[12:13], v[38:39], v[6:7] op_sel_hi:[1,0,1]
	v_pk_add_f32 v[4:5], v[4:5], 1.0 op_sel_hi:[1,0]
	v_pk_fma_f32 v[6:7], v[2:3], v[8:9], v[6:7] op_sel_hi:[0,1,1]
	v_div_scale_f32 v8, s[2:3], v5, v5, v36
	v_rcp_f32_e32 v9, v8
	s_nop 0
	v_fma_f32 v12, -v8, v9, 1.0
	v_fmac_f32_e32 v9, v12, v9
	v_div_scale_f32 v12, vcc, v36, v5, v36
	v_mul_f32_e32 v13, v12, v9
	v_fma_f32 v37, -v8, v13, v12
	v_fmac_f32_e32 v13, v37, v9
	v_fma_f32 v8, -v8, v13, v12
	v_div_fmas_f32 v8, v8, v9, v13
	v_div_fixup_f32 v5, v8, v5, v36
	v_div_scale_f32 v8, s[2:3], v4, v4, v3
	v_rcp_f32_e32 v9, v8
	s_nop 0
	v_fma_f32 v12, -v8, v9, 1.0
	v_fmac_f32_e32 v9, v12, v9
	v_div_scale_f32 v12, vcc, v3, v4, v3
	v_mul_f32_e32 v13, v12, v9
	v_fma_f32 v36, -v8, v13, v12
	v_fmac_f32_e32 v13, v36, v9
	v_fma_f32 v8, -v8, v13, v12
	v_div_fmas_f32 v8, v8, v9, v13
	v_div_fixup_f32 v4, v8, v4, v3
	v_pk_mul_f32 v[4:5], v[6:7], v[4:5]
	v_cvt_pk_bf16_f32 v6, v10, v11
	v_cvt_pk_bf16_f32 v7, v4, v5
	global_store_dwordx2 v[46:47], v[6:7], off offset:32
	s_nop 0
	s_waitcnt vmcnt(5)
; DI unsigned pack2(float a, float b) { f32x2 v = {a, b}; bf16x2_t r = __builtin_convertvector(v, bf16x2_t); return __builtin_bit_cast(unsigned, r); }
; DI float bflo(unsigned v) { return __uint_as_float(v << 16); }
; DI float bfhi(unsigned v) { return __uint_as_float(v & 0xffff0000u); }
; DI size_t blk(size_t row, int k, int R) { return ((size_t)(k >> 5) * R + row) * 32 + (k & 31); }
; DI float silu_f(float x) { return x / (1.f + __expf(-x)); }
; DI void nsa_slc_unit(const Params& p, int u, char* smem, bool probe = false) {
;     ...
;       const int d = 32 * dt + 8 * g4 + 4 * h;
;       bf16_t* gp = p.G + blk(tok, head * 64 + d, NTOK);
;       const u32x2 cv = *(const u32x2*)(oc + d), wv = *(const u32x2*)(ow + d), gv = *(const u32x2*)gp;
;       const float a0 = (g0 * bflo(cv[0]) + g1 * o[dt][4 * g4] + g2 * bflo(wv[0])) * silu_f(bflo(gv[0]));
;       const float a1 = (g0 * bfhi(cv[0]) + g1 * o[dt][4 * g4 + 1] + g2 * bfhi(wv[0])) * silu_f(bfhi(gv[0]));
;       const float a2 = (g0 * bflo(cv[1]) + g1 * o[dt][4 * g4 + 2] + g2 * bflo(wv[1])) * silu_f(bflo(gv[1]));
;       const float a3 = (g0 * bfhi(cv[1]) + g1 * o[dt][4 * g4 + 3] + g2 * bfhi(wv[1])) * silu_f(bfhi(gv[1]));
;       *(u32x2*)gp = (u32x2){pack2(a0, a1), pack2(a2, a3)};
	v_mov_b32_e32 v6, v244
	v_mov_b32_e32 v7, v245
	v_lshlrev_b32_e32 v12, 16, v6
	v_and_b32_e32 v13, 0xffff0000, v6
	s_waitcnt vmcnt(3)
	v_mov_b32_e32 v4, v246
	v_mov_b32_e32 v5, v247
	v_mov_b32_e32 v8, v248
	v_mov_b32_e32 v9, v249
	v_lshlrev_b32_e32 v3, 16, v8
	v_and_b32_e32 v8, 0xffff0000, v8
	v_pk_mul_f32 v[12:13], v[34:35], v[12:13] op_sel_hi:[0,1]
	v_mul_f32_e32 v10, 0xbfb8aa3b, v3
	v_pk_fma_f32 v[12:13], v[14:15], v[38:39], v[12:13] op_sel_hi:[1,0,1]
	v_lshlrev_b32_e32 v14, 16, v4
	v_and_b32_e32 v15, 0xffff0000, v4
	v_mul_f32_e32 v4, 0xbfb8aa3b, v8
	v_exp_f32_e32 v10, v10
	v_exp_f32_e32 v11, v4
	v_pk_fma_f32 v[12:13], v[2:3], v[14:15], v[12:13] op_sel_hi:[0,1,1]
	v_pk_add_f32 v[10:11], v[10:11], 1.0 op_sel_hi:[1,0]
	s_nop 0
	v_div_scale_f32 v4, s[2:3], v11, v11, v8
	v_rcp_f32_e32 v6, v4
	s_nop 0
	v_fma_f32 v14, -v4, v6, 1.0
	v_fmac_f32_e32 v6, v14, v6
	v_div_scale_f32 v14, vcc, v8, v11, v8
	v_mul_f32_e32 v15, v14, v6
	v_fma_f32 v36, -v4, v15, v14
	v_fmac_f32_e32 v15, v36, v6
	v_fma_f32 v4, -v4, v15, v14
	v_div_fmas_f32 v4, v4, v6, v15
	v_div_fixup_f32 v11, v4, v11, v8
	v_div_scale_f32 v4, s[2:3], v10, v10, v3
	v_rcp_f32_e32 v6, v4
	s_nop 0
	v_fma_f32 v8, -v4, v6, 1.0
	v_fmac_f32_e32 v6, v8, v6
	v_div_scale_f32 v8, vcc, v3, v10, v3
	v_mul_f32_e32 v14, v8, v6
	v_fma_f32 v15, -v4, v14, v8
	v_fmac_f32_e32 v14, v15, v6
	v_fma_f32 v4, -v4, v14, v8
	v_div_fmas_f32 v4, v4, v6, v14
	v_div_fixup_f32 v10, v4, v10, v3
	v_pk_mul_f32 v[10:11], v[12:13], v[10:11]
	v_lshlrev_b32_e32 v3, 16, v9
	v_and_b32_e32 v12, 0xffff0000, v9
	v_mul_f32_e32 v4, 0xbfb8aa3b, v3
	v_lshlrev_b32_e32 v8, 16, v5
	v_and_b32_e32 v9, 0xffff0000, v5
	v_mul_f32_e32 v5, 0xbfb8aa3b, v12
	v_exp_f32_e32 v4, v4
	v_exp_f32_e32 v5, v5
	v_lshlrev_b32_e32 v6, 16, v7
	v_and_b32_e32 v7, 0xffff0000, v7
	v_pk_mul_f32 v[6:7], v[34:35], v[6:7] op_sel_hi:[0,1]
	v_pk_fma_f32 v[6:7], v[16:17], v[38:39], v[6:7] op_sel_hi:[1,0,1]
	v_pk_add_f32 v[4:5], v[4:5], 1.0 op_sel_hi:[1,0]
	v_pk_fma_f32 v[6:7], v[2:3], v[8:9], v[6:7] op_sel_hi:[0,1,1]
	v_div_scale_f32 v8, s[2:3], v5, v5, v12
	v_rcp_f32_e32 v9, v8
	s_nop 0
	v_fma_f32 v13, -v8, v9, 1.0
	v_fmac_f32_e32 v9, v13, v9
	v_div_scale_f32 v13, vcc, v12, v5, v12
	v_mul_f32_e32 v14, v13, v9
	v_fma_f32 v15, -v8, v14, v13
	v_fmac_f32_e32 v14, v15, v9
	v_fma_f32 v8, -v8, v14, v13
	v_div_fmas_f32 v8, v8, v9, v14
	v_div_fixup_f32 v5, v8, v5, v12
	v_div_scale_f32 v8, s[2:3], v4, v4, v3
	v_rcp_f32_e32 v9, v8
	s_nop 0
	v_fma_f32 v12, -v8, v9, 1.0
	v_fmac_f32_e32 v9, v12, v9
	v_div_scale_f32 v12, vcc, v3, v4, v3
	v_mul_f32_e32 v13, v12, v9
	v_fma_f32 v14, -v8, v13, v12
	v_fmac_f32_e32 v13, v14, v9
	v_fma_f32 v8, -v8, v13, v12
	v_div_fmas_f32 v8, v8, v9, v13
	v_div_fixup_f32 v4, v8, v4, v3
	v_pk_mul_f32 v[4:5], v[6:7], v[4:5]
	v_cvt_pk_bf16_f32 v6, v10, v11
	v_cvt_pk_bf16_f32 v7, v4, v5
	v_lshl_add_u64 v[4:5], v[180:181], 0, v[0:1]
	v_lshlrev_b64 v[4:5], 6, v[4:5]
	global_store_dwordx2 v[46:47], v[6:7], off offset:48
	v_lshl_add_u64 v[4:5], s[38:39], 0, v[4:5]
	v_lshl_add_u64 v[4:5], v[4:5], 0, v[44:45]
	global_load_dwordx2 v[6:7], v[40:41], off offset:64
	global_load_dwordx2 v[8:9], v[42:43], off offset:64
	global_load_dwordx2 v[10:11], v[4:5], off
	global_load_dwordx2 v[232:233], v[40:41], off offset:80
	global_load_dwordx2 v[234:235], v[42:43], off offset:80
	global_load_dwordx2 v[236:237], v[4:5], off offset:16
	global_load_dwordx2 v[238:239], v[40:41], off offset:96
	global_load_dwordx2 v[240:241], v[42:43], off offset:96
	global_load_dwordx2 v[242:243], v[4:5], off offset:32
	global_load_dwordx2 v[244:245], v[40:41], off offset:112
	global_load_dwordx2 v[246:247], v[42:43], off offset:112
	global_load_dwordx2 v[248:249], v[4:5], off offset:48
	s_waitcnt vmcnt(11)
	v_lshlrev_b32_e32 v14, 16, v6
	v_and_b32_e32 v15, 0xffff0000, v6
	s_waitcnt vmcnt(9)
	v_lshlrev_b32_e32 v0, 16, v10
	v_and_b32_e32 v3, 0xffff0000, v10
	v_mul_f32_e32 v10, 0xbfb8aa3b, v0
	v_mul_f32_e32 v6, 0xbfb8aa3b, v3
	v_exp_f32_e32 v12, v10
	v_exp_f32_e32 v13, v6
	v_lshlrev_b32_e32 v16, 16, v8
	v_and_b32_e32 v17, 0xffff0000, v8
	v_pk_mul_f32 v[14:15], v[34:35], v[14:15] op_sel_hi:[0,1]
	v_pk_add_f32 v[12:13], v[12:13], 1.0 op_sel_hi:[1,0]
	v_pk_fma_f32 v[14:15], v[18:19], v[38:39], v[14:15] op_sel_hi:[1,0,1]
	v_div_scale_f32 v6, s[2:3], v13, v13, v3
	v_rcp_f32_e32 v8, v6
	v_pk_fma_f32 v[14:15], v[2:3], v[16:17], v[14:15] op_sel_hi:[0,1,1]
	v_fma_f32 v10, -v6, v8, 1.0
	v_fmac_f32_e32 v8, v10, v8
	v_div_scale_f32 v10, vcc, v3, v13, v3
	v_mul_f32_e32 v16, v10, v8
	v_fma_f32 v17, -v6, v16, v10
	v_fmac_f32_e32 v16, v17, v8
	v_fma_f32 v6, -v6, v16, v10
	v_div_fmas_f32 v6, v6, v8, v16
	v_div_fixup_f32 v13, v6, v13, v3
	v_div_scale_f32 v3, s[2:3], v12, v12, v0
	v_rcp_f32_e32 v6, v3
	s_nop 0
	v_fma_f32 v8, -v3, v6, 1.0
	v_fmac_f32_e32 v6, v8, v6
	v_div_scale_f32 v8, vcc, v0, v12, v0
	v_mul_f32_e32 v10, v8, v6
	v_fma_f32 v16, -v3, v10, v8
	v_fmac_f32_e32 v10, v16, v6
	v_fma_f32 v3, -v3, v10, v8
	v_div_fmas_f32 v3, v3, v6, v10
	v_div_fixup_f32 v12, v3, v12, v0
	v_lshlrev_b32_e32 v0, 16, v11
	v_and_b32_e32 v3, 0xffff0000, v11
	v_mul_f32_e32 v6, 0xbfb8aa3b, v0
	v_lshlrev_b32_e32 v10, 16, v7
	v_and_b32_e32 v11, 0xffff0000, v7
	v_mul_f32_e32 v7, 0xbfb8aa3b, v3
	v_exp_f32_e32 v6, v6
	v_exp_f32_e32 v7, v7
	v_pk_mul_f32 v[10:11], v[34:35], v[10:11] op_sel_hi:[0,1]
	v_pk_fma_f32 v[10:11], v[20:21], v[38:39], v[10:11] op_sel_hi:[1,0,1]
	v_lshlrev_b32_e32 v8, 16, v9
	v_and_b32_e32 v9, 0xffff0000, v9
	v_pk_add_f32 v[6:7], v[6:7], 1.0 op_sel_hi:[1,0]
	v_pk_fma_f32 v[8:9], v[2:3], v[8:9], v[10:11] op_sel_hi:[0,1,1]
	v_div_scale_f32 v10, s[2:3], v7, v7, v3
	v_rcp_f32_e32 v11, v10
	v_pk_mul_f32 v[12:13], v[14:15], v[12:13]
	v_fma_f32 v14, -v10, v11, 1.0
	v_fmac_f32_e32 v11, v14, v11
	v_div_scale_f32 v14, vcc, v3, v7, v3
	v_mul_f32_e32 v15, v14, v11
	v_fma_f32 v16, -v10, v15, v14
	v_fmac_f32_e32 v15, v16, v11
	v_fma_f32 v10, -v10, v15, v14
	v_div_fmas_f32 v10, v10, v11, v15
	v_div_fixup_f32 v7, v10, v7, v3
	v_div_scale_f32 v3, s[2:3], v6, v6, v0
	v_rcp_f32_e32 v10, v3
	s_nop 0
	v_fma_f32 v11, -v3, v10, 1.0
	v_fmac_f32_e32 v10, v11, v10
	v_div_scale_f32 v11, vcc, v0, v6, v0
	v_mul_f32_e32 v14, v11, v10
	v_fma_f32 v15, -v3, v14, v11
	v_fmac_f32_e32 v14, v15, v10
	v_fma_f32 v3, -v3, v14, v11
	v_div_fmas_f32 v3, v3, v10, v14
	v_div_fixup_f32 v6, v3, v6, v0
	v_pk_mul_f32 v[6:7], v[8:9], v[6:7]
	v_cvt_pk_bf16_f32 v8, v12, v13
	v_cvt_pk_bf16_f32 v9, v6, v7
	global_store_dwordx2 v[4:5], v[8:9], off
	s_nop 0
	s_waitcnt vmcnt(9)
; DI unsigned pack2(float a, float b) { f32x2 v = {a, b}; bf16x2_t r = __builtin_convertvector(v, bf16x2_t); return __builtin_bit_cast(unsigned, r); }
; DI float bflo(unsigned v) { return __uint_as_float(v << 16); }
; DI float bfhi(unsigned v) { return __uint_as_float(v & 0xffff0000u); }
; DI size_t blk(size_t row, int k, int R) { return ((size_t)(k >> 5) * R + row) * 32 + (k & 31); }
; DI float silu_f(float x) { return x / (1.f + __expf(-x)); }
; DI void nsa_slc_unit(const Params& p, int u, char* smem, bool probe = false) {
;     ...
;       const int d = 32 * dt + 8 * g4 + 4 * h;
;       bf16_t* gp = p.G + blk(tok, head * 64 + d, NTOK);
;       const u32x2 cv = *(const u32x2*)(oc + d), wv = *(const u32x2*)(ow + d), gv = *(const u32x2*)gp;
;       const float a0 = (g0 * bflo(cv[0]) + g1 * o[dt][4 * g4] + g2 * bflo(wv[0])) * silu_f(bflo(gv[0]));
;       const float a1 = (g0 * bfhi(cv[0]) + g1 * o[dt][4 * g4 + 1] + g2 * bfhi(wv[0])) * silu_f(bfhi(gv[0]));
;       const float a2 = (g0 * bflo(cv[1]) + g1 * o[dt][4 * g4 + 2] + g2 * bflo(wv[1])) * silu_f(bflo(gv[1]));
;       const float a3 = (g0 * bfhi(cv[1]) + g1 * o[dt][4 * g4 + 3] + g2 * bfhi(wv[1])) * silu_f(bfhi(gv[1]));
;       *(u32x2*)gp = (u32x2){pack2(a0, a1), pack2(a2, a3)};
	v_mov_b32_e32 v8, v232
	v_mov_b32_e32 v9, v233
	v_lshlrev_b32_e32 v14, 16, v8
	s_waitcnt vmcnt(8)
	v_mov_b32_e32 v6, v234
	v_mov_b32_e32 v7, v235
	v_lshlrev_b32_e32 v16, 16, v6
	s_waitcnt vmcnt(7)
	v_mov_b32_e32 v10, v236
	v_mov_b32_e32 v11, v237
	v_lshlrev_b32_e32 v0, 16, v10
	v_and_b32_e32 v3, 0xffff0000, v10
	v_mul_f32_e32 v10, 0xbfb8aa3b, v0
	v_and_b32_e32 v17, 0xffff0000, v6
	v_mul_f32_e32 v6, 0xbfb8aa3b, v3
	v_exp_f32_e32 v12, v10
	v_exp_f32_e32 v13, v6
	v_and_b32_e32 v15, 0xffff0000, v8
	v_pk_mul_f32 v[14:15], v[34:35], v[14:15] op_sel_hi:[0,1]
	v_pk_fma_f32 v[14:15], v[22:23], v[38:39], v[14:15] op_sel_hi:[1,0,1]
	v_pk_add_f32 v[12:13], v[12:13], 1.0 op_sel_hi:[1,0]
	v_pk_fma_f32 v[14:15], v[2:3], v[16:17], v[14:15] op_sel_hi:[0,1,1]
	v_div_scale_f32 v6, s[2:3], v13, v13, v3
	v_rcp_f32_e32 v8, v6
	s_nop 0
	v_fma_f32 v10, -v6, v8, 1.0
	v_fmac_f32_e32 v8, v10, v8
	v_div_scale_f32 v10, vcc, v3, v13, v3
	v_mul_f32_e32 v16, v10, v8
	v_fma_f32 v17, -v6, v16, v10
	v_fmac_f32_e32 v16, v17, v8
	v_fma_f32 v6, -v6, v16, v10
	v_div_fmas_f32 v6, v6, v8, v16
	v_div_fixup_f32 v13, v6, v13, v3
	v_div_scale_f32 v3, s[2:3], v12, v12, v0
	v_rcp_f32_e32 v6, v3
	s_nop 0
	v_fma_f32 v8, -v3, v6, 1.0
	v_fmac_f32_e32 v6, v8, v6
	v_div_scale_f32 v8, vcc, v0, v12, v0
	v_mul_f32_e32 v10, v8, v6
	v_fma_f32 v16, -v3, v10, v8
	v_fmac_f32_e32 v10, v16, v6
	v_fma_f32 v3, -v3, v10, v8
	v_div_fmas_f32 v3, v3, v6, v10
	v_div_fixup_f32 v12, v3, v12, v0
	v_lshlrev_b32_e32 v0, 16, v11
	v_and_b32_e32 v3, 0xffff0000, v11
	v_mul_f32_e32 v6, 0xbfb8aa3b, v0
	v_lshlrev_b32_e32 v10, 16, v7
	v_and_b32_e32 v11, 0xffff0000, v7
	v_mul_f32_e32 v7, 0xbfb8aa3b, v3
	v_exp_f32_e32 v6, v6
	v_exp_f32_e32 v7, v7
	v_lshlrev_b32_e32 v8, 16, v9
	v_and_b32_e32 v9, 0xffff0000, v9
	v_pk_mul_f32 v[8:9], v[34:35], v[8:9] op_sel_hi:[0,1]
	v_pk_fma_f32 v[8:9], v[24:25], v[38:39], v[8:9] op_sel_hi:[1,0,1]
	v_pk_add_f32 v[6:7], v[6:7], 1.0 op_sel_hi:[1,0]
	v_pk_fma_f32 v[8:9], v[2:3], v[10:11], v[8:9] op_sel_hi:[0,1,1]
	v_div_scale_f32 v10, s[2:3], v7, v7, v3
	v_rcp_f32_e32 v11, v10
	v_pk_mul_f32 v[12:13], v[14:15], v[12:13]
	v_fma_f32 v14, -v10, v11, 1.0
	v_fmac_f32_e32 v11, v14, v11
	v_div_scale_f32 v14, vcc, v3, v7, v3
	v_mul_f32_e32 v15, v14, v11
	v_fma_f32 v16, -v10, v15, v14
	v_fmac_f32_e32 v15, v16, v11
	v_fma_f32 v10, -v10, v15, v14
	v_div_fmas_f32 v10, v10, v11, v15
	v_div_fixup_f32 v7, v10, v7, v3
	v_div_scale_f32 v3, s[2:3], v6, v6, v0
	v_rcp_f32_e32 v10, v3
	s_nop 0
	v_fma_f32 v11, -v3, v10, 1.0
	v_fmac_f32_e32 v10, v11, v10
	v_div_scale_f32 v11, vcc, v0, v6, v0
	v_mul_f32_e32 v14, v11, v10
	v_fma_f32 v15, -v3, v14, v11
	v_fmac_f32_e32 v14, v15, v10
	v_fma_f32 v3, -v3, v14, v11
	v_div_fmas_f32 v3, v3, v10, v14
	v_div_fixup_f32 v6, v3, v6, v0
	v_pk_mul_f32 v[6:7], v[8:9], v[6:7]
	v_cvt_pk_bf16_f32 v8, v12, v13
	v_cvt_pk_bf16_f32 v9, v6, v7
	global_store_dwordx2 v[4:5], v[8:9], off offset:16
	s_nop 0
	s_waitcnt vmcnt(7)
	v_mov_b32_e32 v8, v238
	v_mov_b32_e32 v9, v239
	v_lshlrev_b32_e32 v14, 16, v8
	s_waitcnt vmcnt(6)
	v_mov_b32_e32 v6, v240
	v_mov_b32_e32 v7, v241
	v_lshlrev_b32_e32 v16, 16, v6
	s_waitcnt vmcnt(5)
; DI unsigned pack2(float a, float b) { f32x2 v = {a, b}; bf16x2_t r = __builtin_convertvector(v, bf16x2_t); return __builtin_bit_cast(unsigned, r); }
; DI float bflo(unsigned v) { return __uint_as_float(v << 16); }
; DI float bfhi(unsigned v) { return __uint_as_float(v & 0xffff0000u); }
; DI size_t blk(size_t row, int k, int R) { return ((size_t)(k >> 5) * R + row) * 32 + (k & 31); }
; DI float silu_f(float x) { return x / (1.f + __expf(-x)); }
; DI void nsa_slc_unit(const Params& p, int u, char* smem, bool probe = false) {
;     ...
;       const int d = 32 * dt + 8 * g4 + 4 * h;
;       bf16_t* gp = p.G + blk(tok, head * 64 + d, NTOK);
;       const u32x2 cv = *(const u32x2*)(oc + d), wv = *(const u32x2*)(ow + d), gv = *(const u32x2*)gp;
;       const float a0 = (g0 * bflo(cv[0]) + g1 * o[dt][4 * g4] + g2 * bflo(wv[0])) * silu_f(bflo(gv[0]));
;       const float a1 = (g0 * bfhi(cv[0]) + g1 * o[dt][4 * g4 + 1] + g2 * bfhi(wv[0])) * silu_f(bfhi(gv[0]));
;       const float a2 = (g0 * bflo(cv[1]) + g1 * o[dt][4 * g4 + 2] + g2 * bflo(wv[1])) * silu_f(bflo(gv[1]));
;       const float a3 = (g0 * bfhi(cv[1]) + g1 * o[dt][4 * g4 + 3] + g2 * bfhi(wv[1])) * silu_f(bfhi(gv[1]));
;       *(u32x2*)gp = (u32x2){pack2(a0, a1), pack2(a2, a3)};
;     }
	v_mov_b32_e32 v10, v242
	v_mov_b32_e32 v11, v243
	v_lshlrev_b32_e32 v0, 16, v10
	v_and_b32_e32 v3, 0xffff0000, v10
	v_mul_f32_e32 v10, 0xbfb8aa3b, v0
	v_and_b32_e32 v17, 0xffff0000, v6
	v_mul_f32_e32 v6, 0xbfb8aa3b, v3
	v_exp_f32_e32 v12, v10
	v_exp_f32_e32 v13, v6
	v_and_b32_e32 v15, 0xffff0000, v8
	v_pk_mul_f32 v[14:15], v[34:35], v[14:15] op_sel_hi:[0,1]
	v_pk_fma_f32 v[14:15], v[26:27], v[38:39], v[14:15] op_sel_hi:[1,0,1]
	v_pk_add_f32 v[12:13], v[12:13], 1.0 op_sel_hi:[1,0]
	v_pk_fma_f32 v[14:15], v[2:3], v[16:17], v[14:15] op_sel_hi:[0,1,1]
	v_div_scale_f32 v6, s[2:3], v13, v13, v3
	v_rcp_f32_e32 v8, v6
	s_nop 0
	v_fma_f32 v10, -v6, v8, 1.0
	v_fmac_f32_e32 v8, v10, v8
	v_div_scale_f32 v10, vcc, v3, v13, v3
	v_mul_f32_e32 v16, v10, v8
	v_fma_f32 v17, -v6, v16, v10
	v_fmac_f32_e32 v16, v17, v8
	v_fma_f32 v6, -v6, v16, v10
	v_div_fmas_f32 v6, v6, v8, v16
	v_div_fixup_f32 v13, v6, v13, v3
	v_div_scale_f32 v3, s[2:3], v12, v12, v0
	v_rcp_f32_e32 v6, v3
	s_nop 0
	v_fma_f32 v8, -v3, v6, 1.0
	v_fmac_f32_e32 v6, v8, v6
	v_div_scale_f32 v8, vcc, v0, v12, v0
	v_mul_f32_e32 v10, v8, v6
	v_fma_f32 v16, -v3, v10, v8
	v_fmac_f32_e32 v10, v16, v6
	v_fma_f32 v3, -v3, v10, v8
	v_div_fmas_f32 v3, v3, v6, v10
	v_div_fixup_f32 v12, v3, v12, v0
	v_lshlrev_b32_e32 v0, 16, v11
	v_and_b32_e32 v3, 0xffff0000, v11
	v_mul_f32_e32 v6, 0xbfb8aa3b, v0
	v_lshlrev_b32_e32 v10, 16, v7
	v_and_b32_e32 v11, 0xffff0000, v7
	v_mul_f32_e32 v7, 0xbfb8aa3b, v3
	v_exp_f32_e32 v6, v6
	v_exp_f32_e32 v7, v7
	v_lshlrev_b32_e32 v8, 16, v9
	v_and_b32_e32 v9, 0xffff0000, v9
	v_pk_mul_f32 v[8:9], v[34:35], v[8:9] op_sel_hi:[0,1]
	v_pk_fma_f32 v[8:9], v[28:29], v[38:39], v[8:9] op_sel_hi:[1,0,1]
	v_pk_add_f32 v[6:7], v[6:7], 1.0 op_sel_hi:[1,0]
	v_pk_fma_f32 v[8:9], v[2:3], v[10:11], v[8:9] op_sel_hi:[0,1,1]
	v_div_scale_f32 v10, s[2:3], v7, v7, v3
	v_rcp_f32_e32 v11, v10
	v_pk_mul_f32 v[12:13], v[14:15], v[12:13]
	v_fma_f32 v14, -v10, v11, 1.0
	v_fmac_f32_e32 v11, v14, v11
	v_div_scale_f32 v14, vcc, v3, v7, v3
	v_mul_f32_e32 v15, v14, v11
	v_fma_f32 v16, -v10, v15, v14
	v_fmac_f32_e32 v15, v16, v11
	v_fma_f32 v10, -v10, v15, v14
	v_div_fmas_f32 v10, v10, v11, v15
	v_div_fixup_f32 v7, v10, v7, v3
	v_div_scale_f32 v3, s[2:3], v6, v6, v0
	v_rcp_f32_e32 v10, v3
	s_nop 0
	v_fma_f32 v11, -v3, v10, 1.0
	v_fmac_f32_e32 v10, v11, v10
	v_div_scale_f32 v11, vcc, v0, v6, v0
	v_mul_f32_e32 v14, v11, v10
	v_fma_f32 v15, -v3, v14, v11
	v_fmac_f32_e32 v14, v15, v10
	v_fma_f32 v3, -v3, v14, v11
	v_div_fmas_f32 v3, v3, v10, v14
	v_div_fixup_f32 v6, v3, v6, v0
	v_pk_mul_f32 v[6:7], v[8:9], v[6:7]
	v_cvt_pk_bf16_f32 v8, v12, v13
	v_cvt_pk_bf16_f32 v9, v6, v7
	global_store_dwordx2 v[4:5], v[8:9], off offset:32
	s_nop 0
	s_waitcnt vmcnt(5)
	v_mov_b32_e32 v8, v244
	v_mov_b32_e32 v9, v245
	v_lshlrev_b32_e32 v14, 16, v8
	s_waitcnt vmcnt(4)
	v_mov_b32_e32 v6, v246
	v_mov_b32_e32 v7, v247
	v_lshlrev_b32_e32 v16, 16, v6
	s_waitcnt vmcnt(3)
	v_mov_b32_e32 v10, v248
	v_mov_b32_e32 v11, v249
	v_lshlrev_b32_e32 v0, 16, v10
	v_and_b32_e32 v3, 0xffff0000, v10
	v_mul_f32_e32 v10, 0xbfb8aa3b, v0
	v_and_b32_e32 v17, 0xffff0000, v6
	v_mul_f32_e32 v6, 0xbfb8aa3b, v3
	v_exp_f32_e32 v12, v10
	v_exp_f32_e32 v13, v6
	v_and_b32_e32 v15, 0xffff0000, v8
	v_pk_mul_f32 v[14:15], v[34:35], v[14:15] op_sel_hi:[0,1]
	v_pk_fma_f32 v[14:15], v[30:31], v[38:39], v[14:15] op_sel_hi:[1,0,1]
	v_pk_add_f32 v[12:13], v[12:13], 1.0 op_sel_hi:[1,0]
	v_pk_fma_f32 v[14:15], v[2:3], v[16:17], v[14:15] op_sel_hi:[0,1,1]
	v_div_scale_f32 v6, s[2:3], v13, v13, v3
	v_rcp_f32_e32 v8, v6
	s_nop 0
	v_fma_f32 v10, -v6, v8, 1.0
	v_fmac_f32_e32 v8, v10, v8
	v_div_scale_f32 v10, vcc, v3, v13, v3
	v_mul_f32_e32 v16, v10, v8
	v_fma_f32 v17, -v6, v16, v10
	v_fmac_f32_e32 v16, v17, v8
	v_fma_f32 v6, -v6, v16, v10
	v_div_fmas_f32 v6, v6, v8, v16
	v_div_fixup_f32 v13, v6, v13, v3
	v_div_scale_f32 v3, s[2:3], v12, v12, v0
	v_rcp_f32_e32 v6, v3
	s_nop 0
	v_fma_f32 v8, -v3, v6, 1.0
	v_fmac_f32_e32 v6, v8, v6
	v_div_scale_f32 v8, vcc, v0, v12, v0
	v_mul_f32_e32 v10, v8, v6
	v_fma_f32 v16, -v3, v10, v8
	v_fmac_f32_e32 v10, v16, v6
	v_fma_f32 v3, -v3, v10, v8
	v_div_fmas_f32 v3, v3, v6, v10
	v_div_fixup_f32 v12, v3, v12, v0
	v_pk_mul_f32 v[12:13], v[14:15], v[12:13]
	v_lshlrev_b32_e32 v0, 16, v11
	v_and_b32_e32 v14, 0xffff0000, v11
	v_mul_f32_e32 v3, 0xbfb8aa3b, v0
	v_lshlrev_b32_e32 v10, 16, v7
	v_and_b32_e32 v11, 0xffff0000, v7
	v_mul_f32_e32 v7, 0xbfb8aa3b, v14
	v_exp_f32_e32 v6, v3
	v_exp_f32_e32 v7, v7
	v_lshlrev_b32_e32 v8, 16, v9
	v_and_b32_e32 v9, 0xffff0000, v9
	v_pk_mul_f32 v[8:9], v[34:35], v[8:9] op_sel_hi:[0,1]
	v_pk_fma_f32 v[8:9], v[32:33], v[38:39], v[8:9] op_sel_hi:[1,0,1]
	v_pk_add_f32 v[6:7], v[6:7], 1.0 op_sel_hi:[1,0]
	v_pk_fma_f32 v[2:3], v[2:3], v[10:11], v[8:9] op_sel_hi:[0,1,1]
	v_div_scale_f32 v8, s[2:3], v7, v7, v14
	v_rcp_f32_e32 v9, v8
	s_nop 0
	v_fma_f32 v10, -v8, v9, 1.0
	v_fmac_f32_e32 v9, v10, v9
	v_div_scale_f32 v10, vcc, v14, v7, v14
	v_mul_f32_e32 v11, v10, v9
	v_fma_f32 v15, -v8, v11, v10
	v_fmac_f32_e32 v11, v15, v9
	v_fma_f32 v8, -v8, v11, v10
	v_div_fmas_f32 v8, v8, v9, v11
	v_div_fixup_f32 v7, v8, v7, v14
	v_div_scale_f32 v8, s[2:3], v6, v6, v0
	v_rcp_f32_e32 v9, v8
	s_nop 0
	v_fma_f32 v10, -v8, v9, 1.0
	v_fmac_f32_e32 v9, v10, v9
	v_div_scale_f32 v10, vcc, v0, v6, v0
	v_mul_f32_e32 v11, v10, v9
	v_fma_f32 v14, -v8, v11, v10
	v_fmac_f32_e32 v11, v14, v9
	v_fma_f32 v8, -v8, v11, v10
	v_div_fmas_f32 v8, v8, v9, v11
	v_div_fixup_f32 v6, v8, v6, v0
	v_pk_mul_f32 v[2:3], v[2:3], v[6:7]
	v_cvt_pk_bf16_f32 v6, v12, v13
	v_cvt_pk_bf16_f32 v7, v2, v3
	global_store_dwordx2 v[4:5], v[6:7], off offset:48
	s_cbranch_scc0 .LBB0_729
